# CONV loop with 8 channels per thread and iteration (16-byte row loads and store): half the iterations of the 4-channel loop
# speedup vs baseline: 1.0074x; 1.0016x over previous
.LBB0_1231:
	s_andn2_b64 vcc, exec, s[0:1]
	s_cbranch_vccnz .LBB0_1289
	s_cmp_gt_i32 s79, 9
	s_mov_b64 s[0:1], -1
	s_cbranch_scc0 .LBB0_1237
	v_mov_b32_e32 v0, s63
	ds_read_b32 v0, v0
	s_add_i32 s2, s91, 0x20050
	s_waitcnt lgkmcnt(0)
	v_readfirstlane_b32 s0, v0
	v_mov_b32_e32 v0, s89
	ds_read_b32 v0, v0
	s_waitcnt lgkmcnt(0)
	v_readfirstlane_b32 s1, v0
	v_mov_b32_e32 v0, s2
	ds_read_b32 v0, v0
	s_add_i32 s2, s91, 0x20054
	s_waitcnt lgkmcnt(0)
	v_readfirstlane_b32 s4, v0
	v_mov_b32_e32 v0, s2
	ds_read_b32 v0, v0
	s_add_i32 s2, s91, 0x20058
	s_waitcnt lgkmcnt(0)
	v_readfirstlane_b32 s5, v0
	v_mov_b32_e32 v0, s2
	ds_read_b32 v0, v0
	s_add_i32 s2, s91, 0x2005c
	s_waitcnt lgkmcnt(0)
	v_readfirstlane_b32 s6, v0
	v_mov_b32_e32 v0, s2
	ds_read_b32 v0, v0
	s_mov_b32 s2, 0x420000
	v_cmp_gt_i32_e32 vcc, s2, v160
	s_waitcnt lgkmcnt(0)
	v_readfirstlane_b32 s7, v0
	s_and_saveexec_b64 s[2:3], vcc
	s_cbranch_execz .LBB0_1236
	v_readlane_b32 s9, v254, 26
	s_lshl_b32 s8, s9, 12
	s_lshl_b32 s9, s9, 14
	s_add_u32 s4, s4, s9
	s_addc_u32 s5, s5, 0
	s_add_u32 s6, s6, s8
	s_addc_u32 s7, s7, 0
	s_add_u32 s8, s0, 0x4200000
	s_addc_u32 s9, s1, 0
	s_add_u32 s10, s0, 0x8400000
	s_addc_u32 s11, s1, 0
	s_mov_b64 s[12:13], 0
	v_mov_b32_e32 v12, v160
	v_lshlrev_b32_e32 v62, 3, v160
	v_and_b32_e32 v62, 0x3f8, v62
	v_lshlrev_b32_e32 v62, 2, v62
	v_add_u32_e32 v63, 0x1000, v62
	v_add_u32_e32 v104, 0x2000, v62
	v_add_u32_e32 v105, 0x3000, v62
	global_load_dwordx4 v[64:67], v62, s[6:7]
	global_load_dwordx4 v[68:71], v62, s[6:7] offset:16
	global_load_dwordx4 v[72:75], v62, s[4:5]
	global_load_dwordx4 v[76:79], v62, s[4:5] offset:16
	global_load_dwordx4 v[80:83], v63, s[4:5]
	global_load_dwordx4 v[84:87], v63, s[4:5] offset:16
	global_load_dwordx4 v[88:91], v104, s[4:5]
	global_load_dwordx4 v[92:95], v104, s[4:5] offset:16
	global_load_dwordx4 v[96:99], v105, s[4:5]
	global_load_dwordx4 v[100:103], v105, s[4:5] offset:16
.LBB0_1235:
	v_ashrrev_i32_e32 v0, 7, v12
	v_cmp_gt_i32_e32 vcc, s92, v0
	v_mov_b32_e32 v2, 0x7fffff00
	v_mov_b32_e32 v3, 0xffffe000
	v_cndmask_b32_e32 v2, v2, v3, vcc
	v_cndmask_b32_e32 v3, v227, v238, vcc
	v_cndmask_b32_e32 v13, v155, v253, vcc
	v_and_b32_e32 v28, v3, v0
	v_and_b32_e32 v25, v2, v0
	v_lshlrev_b32_e32 v1, 3, v12
	v_and_b32_e32 v1, 0x3f8, v1
	v_lshlrev_b32_e32 v2, 1, v1
	v_mov_b32_e32 v3, v153
	v_lshl_add_u64 v[6:7], s[8:9], 0, v[2:3]
	v_add_u32_e32 v30, -2, v28
	v_cmp_lt_u32_e32 vcc, 1, v28
	v_cmp_lt_u32_e64 s[0:1], v30, v13
	s_and_b64 vcc, vcc, s[0:1]
	v_cndmask_b32_e32 v30, v28, v30, vcc
	v_cndmask_b32_e64 v40, 0, 1.0, vcc
	v_add_u32_e32 v30, v30, v25
	v_ashrrev_i32_e32 v31, 31, v30
	v_lshlrev_b64 v[30:31], 11, v[30:31]
	v_lshl_add_u64 v[30:31], v[6:7], 0, v[30:31]
	global_load_dwordx4 v[48:51], v[30:31], off
	v_add_u32_e32 v32, -1, v28
	v_cmp_lt_u32_e32 vcc, v32, v13
	s_nop 1
	v_cndmask_b32_e64 v42, 0, 1.0, vcc
	v_add_u32_e32 v18, v25, v28
	s_nop 1
	v_subbrev_co_u32_e64 v32, s[0:1], 0, v18, vcc
	v_ashrrev_i32_e32 v33, 31, v32
	v_lshlrev_b64 v[32:33], 11, v[32:33]
	v_lshl_add_u64 v[32:33], v[6:7], 0, v[32:33]
	global_load_dwordx4 v[52:55], v[32:33], off
	v_cmp_lt_u32_e32 vcc, v28, v13
	s_nop 1
	v_cndmask_b32_e64 v44, 0, 1.0, vcc
	v_ashrrev_i32_e32 v19, 31, v18
	v_lshlrev_b64 v[34:35], 11, v[18:19]
	v_lshl_add_u64 v[34:35], v[6:7], 0, v[34:35]
	global_load_dwordx4 v[56:59], v[34:35], off
	v_add_u32_e32 v36, 1, v28
	v_cmp_lt_u32_e32 vcc, v36, v13
	s_nop 1
	v_cndmask_b32_e32 v36, v28, v36, vcc
	v_cndmask_b32_e64 v46, 0, 1.0, vcc
	v_add_u32_e32 v36, v36, v25
	v_ashrrev_i32_e32 v37, 31, v36
	v_lshlrev_b64 v[36:37], 11, v[36:37]
	v_lshl_add_u64 v[36:37], v[6:7], 0, v[36:37]
	global_load_dwordx4 v[106:109], v[36:37], off
	v_ashrrev_i32_e32 v1, 31, v0
	v_lshlrev_b64 v[0:1], 11, v[0:1]
	v_lshl_add_u64 v[0:1], s[10:11], 0, v[0:1]
	v_lshl_add_u64 v[0:1], v[0:1], 0, v[2:3]
	v_add_u32_e32 v12, s24, v12
	v_cmp_lt_i32_e32 vcc, 0x20ffff, v12
	s_nop 1
	s_or_b64 s[12:13], vcc, s[12:13]
	s_waitcnt vmcnt(3)
	v_lshlrev_b32_e32 v20, 16, v48
	v_and_b32_e32 v21, 0xffff0000, v48
	v_lshlrev_b32_e32 v22, 16, v49
	v_and_b32_e32 v23, 0xffff0000, v49
	v_lshlrev_b32_e32 v24, 16, v50
	v_and_b32_e32 v25, 0xffff0000, v50
	v_lshlrev_b32_e32 v26, 16, v51
	v_and_b32_e32 v27, 0xffff0000, v51
	v_pk_mul_f32 v[14:15], v[72:73], v[20:21]
	v_pk_fma_f32 v[14:15], v[14:15], v[40:41], v[64:65] op_sel_hi:[1,0,1]
	v_pk_mul_f32 v[16:17], v[74:75], v[22:23]
	v_pk_fma_f32 v[16:17], v[16:17], v[40:41], v[66:67] op_sel_hi:[1,0,1]
	v_pk_mul_f32 v[110:111], v[76:77], v[24:25]
	v_pk_fma_f32 v[110:111], v[110:111], v[40:41], v[68:69] op_sel_hi:[1,0,1]
	v_pk_mul_f32 v[112:113], v[78:79], v[26:27]
	v_pk_fma_f32 v[112:113], v[112:113], v[40:41], v[70:71] op_sel_hi:[1,0,1]
	s_waitcnt vmcnt(2)
	v_lshlrev_b32_e32 v20, 16, v52
	v_and_b32_e32 v21, 0xffff0000, v52
	v_lshlrev_b32_e32 v22, 16, v53
	v_and_b32_e32 v23, 0xffff0000, v53
	v_lshlrev_b32_e32 v24, 16, v54
	v_and_b32_e32 v25, 0xffff0000, v54
	v_lshlrev_b32_e32 v26, 16, v55
	v_and_b32_e32 v27, 0xffff0000, v55
	v_pk_mul_f32 v[8:9], v[80:81], v[20:21]
	v_pk_fma_f32 v[14:15], v[42:43], v[8:9], v[14:15] op_sel_hi:[0,1,1]
	v_pk_mul_f32 v[10:11], v[82:83], v[22:23]
	v_pk_fma_f32 v[16:17], v[42:43], v[10:11], v[16:17] op_sel_hi:[0,1,1]
	v_pk_mul_f32 v[118:119], v[84:85], v[24:25]
	v_pk_fma_f32 v[110:111], v[42:43], v[118:119], v[110:111] op_sel_hi:[0,1,1]
	v_pk_mul_f32 v[120:121], v[86:87], v[26:27]
	v_pk_fma_f32 v[112:113], v[42:43], v[120:121], v[112:113] op_sel_hi:[0,1,1]
	s_waitcnt vmcnt(1)
	v_lshlrev_b32_e32 v20, 16, v56
	v_and_b32_e32 v21, 0xffff0000, v56
	v_lshlrev_b32_e32 v22, 16, v57
	v_and_b32_e32 v23, 0xffff0000, v57
	v_lshlrev_b32_e32 v24, 16, v58
	v_and_b32_e32 v25, 0xffff0000, v58
	v_lshlrev_b32_e32 v26, 16, v59
	v_and_b32_e32 v27, 0xffff0000, v59
	v_pk_mul_f32 v[8:9], v[88:89], v[20:21]
	v_pk_fma_f32 v[14:15], v[44:45], v[8:9], v[14:15] op_sel_hi:[0,1,1]
	v_pk_mul_f32 v[10:11], v[90:91], v[22:23]
	v_pk_fma_f32 v[16:17], v[44:45], v[10:11], v[16:17] op_sel_hi:[0,1,1]
	v_pk_mul_f32 v[118:119], v[92:93], v[24:25]
	v_pk_fma_f32 v[110:111], v[44:45], v[118:119], v[110:111] op_sel_hi:[0,1,1]
	v_pk_mul_f32 v[120:121], v[94:95], v[26:27]
	v_pk_fma_f32 v[112:113], v[44:45], v[120:121], v[112:113] op_sel_hi:[0,1,1]
	s_waitcnt vmcnt(0)
	v_lshlrev_b32_e32 v20, 16, v106
	v_and_b32_e32 v21, 0xffff0000, v106
	v_lshlrev_b32_e32 v22, 16, v107
	v_and_b32_e32 v23, 0xffff0000, v107
	v_lshlrev_b32_e32 v24, 16, v108
	v_and_b32_e32 v25, 0xffff0000, v108
	v_lshlrev_b32_e32 v26, 16, v109
	v_and_b32_e32 v27, 0xffff0000, v109
	v_pk_mul_f32 v[8:9], v[96:97], v[20:21]
	v_pk_fma_f32 v[14:15], v[46:47], v[8:9], v[14:15] op_sel_hi:[0,1,1]
	v_pk_mul_f32 v[10:11], v[98:99], v[22:23]
	v_pk_fma_f32 v[16:17], v[46:47], v[10:11], v[16:17] op_sel_hi:[0,1,1]
	v_pk_mul_f32 v[118:119], v[100:101], v[24:25]
	v_pk_fma_f32 v[110:111], v[46:47], v[118:119], v[110:111] op_sel_hi:[0,1,1]
	v_pk_mul_f32 v[120:121], v[102:103], v[26:27]
	v_pk_fma_f32 v[112:113], v[46:47], v[120:121], v[112:113] op_sel_hi:[0,1,1]
	v_cvt_pk_bf16_f32 v114, v14, v15
	v_cvt_pk_bf16_f32 v115, v16, v17
	v_cvt_pk_bf16_f32 v116, v110, v111
	v_cvt_pk_bf16_f32 v117, v112, v113
	global_store_dwordx4 v[0:1], v[114:117], off
	s_andn2_b64 exec, exec, s[12:13]
	s_cbranch_execnz .LBB0_1235
